# pu/pv fp8-table and p->bf16 conversions moved out of phase 0 into the mixer phase: the 448 non-scan workgroups run them after their attention items while the DeltaNet scan (critical path) finishes
# speedup vs baseline: 1.2014x; 1.0256x over previous
; __device__ void ph_prep(const P& p, float* lds) {
;     ...
;     } else if (it < NTR + NCV) {
;       int j = it - NTR;
;       if (j < 16) conv_chunk4(p.keys1, p_K1b, (size_t)j * 8192);
;       else if ((j -= 16) < 16) conv_chunk4(p.keys2, p_K2b, (size_t)j * 8192);
;       else if ((j -= 16) < 2048) conv_table_chunk4(p.pu, p_U8, (size_t)j * 8192, SU);
;       else if ((j -= 2048) < 2048) conv_table_chunk4(p.pv, p_V8, (size_t)j * 8192, SV);
;       else if ((j -= 2048) < 1024) conv_chunk4(p.p_p, p_Pb, (size_t)j * 8192);
;       else { j -= 1024; conv_chunk4(p.p_s, p_Pb + (size_t)TP * 256, (size_t)j * 8192); }
.LBB0_17:
	s_andn2_b64 vcc, exec, s[34:35]
	s_cbranch_vccnz .LBB0_38
	s_cmpk_gt_u32 s36, 0x72f
	s_mov_b64 s[34:35], -1
	s_cbranch_scc0 .LBB0_36
	s_cmpk_gt_u32 s36, 0x73f
	s_cbranch_scc0 .LBB0_33
	s_branch .LBB0_38

; __device__ __forceinline__ int tid_() { int t = threadIdx.x; asm volatile("" : "+v"(t)); return t; }
; __device__ __forceinline__ void conv_chunk4(const float* __restrict__ src, u16* __restrict__ dst, size_t base) {
;   f32x4 a[4], b[4];
; #pragma unroll
;   for (int q = 0; q < 4; ++q) {
;     size_t i = base + (size_t)q * 2048 + (size_t)tid_() * 8;
;     a[q] = *(const f32x4*)(src + i); b[q] = *(const f32x4*)(src + i + 4);
;   }
; #pragma unroll
;   for (int q = 0; q < 4; ++q) {
;     size_t i = base + (size_t)q * 2048 + (size_t)tid_() * 8;
;     BF8 t; t.u[0] = pack2(a[q][0], a[q][1]); t.u[1] = pack2(a[q][2], a[q][3]); t.u[2] = pack2(b[q][0], b[q][1]); t.u[3] = pack2(b[q][2], b[q][3]);
;     *(uint4*)(dst + i) = t.q;
;   }
; }
; __device__ __forceinline__ void conv_table_chunk4(const float* __restrict__ src, unsigned char* __restrict__ dst, size_t base, float scale) {
;   f32x4 a[4], b[4];
; #pragma unroll
;   for (int q = 0; q < 4; ++q) {
;     size_t i = base + (size_t)q * 2048 + (size_t)tid_() * 8;
;     a[q] = *(const f32x4*)(src + i); b[q] = *(const f32x4*)(src + i + 4);
;   }
; #pragma unroll
;   for (int q = 0; q < 4; ++q) {
;     size_t i = base + (size_t)q * 2048 + (size_t)tid_() * 8;
;     int w0 = 0, w1 = 0;
;     w0 = __builtin_amdgcn_cvt_pk_fp8_f32(a[q][0] * scale, a[q][1] * scale, w0, false);
;     w0 = __builtin_amdgcn_cvt_pk_fp8_f32(a[q][2] * scale, a[q][3] * scale, w0, true);
;     w1 = __builtin_amdgcn_cvt_pk_fp8_f32(b[q][0] * scale, b[q][1] * scale, w1, false);
;     w1 = __builtin_amdgcn_cvt_pk_fp8_f32(b[q][2] * scale, b[q][3] * scale, w1, true);
;     size_t e = i >> 10; int col = (int)(i & 1023); int x = col >> 7;
;     *(uint2*)(dst + ((size_t)x * 16384 + e) * 128 + (col & 127)) = make_uint2((unsigned)w0, (unsigned)w1);
;   }
; }
.LBB0_478:
	s_and_b64 vcc, exec, s[0:1]
	s_cbranch_vccnz .Lscan_go
	v_readlane_b32 s50, v228, 0
	v_readlane_b32 s51, v228, 10
	v_readlane_b32 s40, v228, 8
	v_readlane_b32 s41, v228, 9
	v_readlane_b32 s42, v228, 57
	v_readlane_b32 s43, v228, 58
	v_readlane_b32 s44, v228, 59
	v_readlane_b32 s45, v228, 60
	v_readlane_b32 s46, v228, 21
	v_readlane_b32 s47, v228, 22
	v_readlane_b32 s48, v228, 23
	v_readlane_b32 s49, v228, 24
	s_sub_u32 s50, s50, 32
	s_sub_u32 s51, s51, 32
	v_lshlrev_b32_e32 v1, 5, v220
	v_add_u32_e32 v5, 0x2000, v1
	v_add_u32_e32 v6, 0x4000, v1
	v_add_u32_e32 v7, 0x6000, v1
	v_lshlrev_b32_e32 v3, 4, v220
	v_add_u32_e32 v9, 0x1000, v3
	v_add_u32_e32 v10, 0x2000, v3
	v_add_u32_e32 v11, 0x3000, v3
	v_bfe_u32 v2, v220, 4, 3
	v_lshlrev_b32_e32 v2, 21, v2
	v_lshrrev_b32_e32 v12, 7, v220
	v_lshl_or_b32 v2, v12, 7, v2
	v_and_b32_e32 v12, 15, v220
	v_lshl_or_b32 v2, v12, 3, v2
	v_mov_b32_e32 v13, 0
.Ldef_loop:
	s_cmp_ge_u32 s50, 5152
	s_cbranch_scc1 .Ldef_done
	s_cmp_ge_u32 s50, 4096
	s_cbranch_scc1 .Ldef_p
	s_cmp_ge_u32 s50, 2048
	s_cbranch_scc1 .Ldef_pv
	s_mov_b32 s52, s50
	s_mov_b64 s[54:55], s[42:43]
	s_mov_b32 s58, 0x42800000
	s_mov_b32 s59, 0xec0000
	s_branch .Ldef_tab
.Ldef_pv:
	s_sub_u32 s52, s50, 2048
	s_mov_b64 s[54:55], s[44:45]
	s_mov_b32 s58, 0x41800000
	s_mov_b32 s59, 0x1ec0000
.Ldef_tab:
	s_mov_b32 s53, 0
	s_lshl_b64 s[60:61], s[52:53], 15
	s_add_u32 s54, s54, s60
	s_addc_u32 s55, s55, s61
	s_lshl_b32 s60, s52, 10
	s_add_u32 s60, s60, s59
	s_add_u32 s56, s40, s60
	s_addc_u32 s57, s41, 0
	global_load_dwordx4 v[16:19], v1, s[54:55]
	global_load_dwordx4 v[20:23], v1, s[54:55] offset:16
	global_load_dwordx4 v[24:27], v5, s[54:55]
	global_load_dwordx4 v[28:31], v5, s[54:55] offset:16
	global_load_dwordx4 v[32:35], v6, s[54:55]
	global_load_dwordx4 v[36:39], v6, s[54:55] offset:16
	global_load_dwordx4 v[40:43], v7, s[54:55]
	global_load_dwordx4 v[44:47], v7, s[54:55] offset:16
	s_waitcnt vmcnt(6)
	v_mul_f32_e32 v16, s58, v16
	v_mul_f32_e32 v17, s58, v17
	v_mul_f32_e32 v18, s58, v18
	v_mul_f32_e32 v19, s58, v19
	v_mul_f32_e32 v20, s58, v20
	v_mul_f32_e32 v21, s58, v21
	v_mul_f32_e32 v22, s58, v22
	v_mul_f32_e32 v23, s58, v23
	v_mov_b32_e32 v48, 0
	v_mov_b32_e32 v49, 0
	v_cvt_pk_fp8_f32 v48, v16, v17
	v_cvt_pk_fp8_f32 v49, v20, v21
	s_nop 0
	v_cvt_pk_fp8_f32 v48, v18, v19 op_sel:[0,0,1]
	v_cvt_pk_fp8_f32 v49, v22, v23 op_sel:[0,0,1]
	s_nop 1
	global_store_dwordx2 v2, v[48:49], s[56:57] offset:0
	s_waitcnt vmcnt(4)
	v_mul_f32_e32 v24, s58, v24
	v_mul_f32_e32 v25, s58, v25
	v_mul_f32_e32 v26, s58, v26
	v_mul_f32_e32 v27, s58, v27
	v_mul_f32_e32 v28, s58, v28
	v_mul_f32_e32 v29, s58, v29
	v_mul_f32_e32 v30, s58, v30
	v_mul_f32_e32 v31, s58, v31
	v_mov_b32_e32 v50, 0
	v_mov_b32_e32 v51, 0
	v_cvt_pk_fp8_f32 v50, v24, v25
	v_cvt_pk_fp8_f32 v51, v28, v29
	s_nop 0
	v_cvt_pk_fp8_f32 v50, v26, v27 op_sel:[0,0,1]
	v_cvt_pk_fp8_f32 v51, v30, v31 op_sel:[0,0,1]
	s_nop 1
	global_store_dwordx2 v2, v[50:51], s[56:57] offset:256
	s_waitcnt vmcnt(2)
	v_mul_f32_e32 v32, s58, v32
	v_mul_f32_e32 v33, s58, v33
	v_mul_f32_e32 v34, s58, v34
	v_mul_f32_e32 v35, s58, v35
	v_mul_f32_e32 v36, s58, v36
	v_mul_f32_e32 v37, s58, v37
	v_mul_f32_e32 v38, s58, v38
	v_mul_f32_e32 v39, s58, v39
	v_mov_b32_e32 v52, 0
	v_mov_b32_e32 v53, 0
	v_cvt_pk_fp8_f32 v52, v32, v33
	v_cvt_pk_fp8_f32 v53, v36, v37
	s_nop 0
	v_cvt_pk_fp8_f32 v52, v34, v35 op_sel:[0,0,1]
	v_cvt_pk_fp8_f32 v53, v38, v39 op_sel:[0,0,1]
	s_nop 1
	global_store_dwordx2 v2, v[52:53], s[56:57] offset:512
	s_waitcnt vmcnt(0)
	v_mul_f32_e32 v40, s58, v40
	v_mul_f32_e32 v41, s58, v41
	v_mul_f32_e32 v42, s58, v42
	v_mul_f32_e32 v43, s58, v43
	v_mul_f32_e32 v44, s58, v44
	v_mul_f32_e32 v45, s58, v45
	v_mul_f32_e32 v46, s58, v46
	v_mul_f32_e32 v47, s58, v47
	v_mov_b32_e32 v54, 0
	v_mov_b32_e32 v55, 0
	v_cvt_pk_fp8_f32 v54, v40, v41
	v_cvt_pk_fp8_f32 v55, v44, v45
	s_nop 0
	v_cvt_pk_fp8_f32 v54, v42, v43 op_sel:[0,0,1]
	v_cvt_pk_fp8_f32 v55, v46, v47 op_sel:[0,0,1]
	s_nop 1
	global_store_dwordx2 v2, v[54:55], s[56:57] offset:768
	s_branch .Ldef_next
.Ldef_p:
	s_sub_u32 s52, s50, 4096
	s_mov_b32 s53, 0
	s_lshl_b64 s[60:61], s[52:53], 14
	s_add_u32 s56, s40, s60
	s_addc_u32 s57, s41, s61
	s_add_u32 s56, s56, 0x2ec0000
	s_addc_u32 s57, s57, 0
	s_mov_b64 s[54:55], s[46:47]
	s_cmp_lt_u32 s52, 1024
	s_cbranch_scc1 .Ldef_psrc
	s_sub_u32 s52, s52, 1024
	s_mov_b64 s[54:55], s[48:49]
.Ldef_psrc:
	s_lshl_b64 s[60:61], s[52:53], 15
	s_add_u32 s54, s54, s60
	s_addc_u32 s55, s55, s61
	global_load_dwordx4 v[16:19], v1, s[54:55]
	global_load_dwordx4 v[20:23], v1, s[54:55] offset:16
	global_load_dwordx4 v[24:27], v5, s[54:55]
	global_load_dwordx4 v[28:31], v5, s[54:55] offset:16
	global_load_dwordx4 v[32:35], v6, s[54:55]
	global_load_dwordx4 v[36:39], v6, s[54:55] offset:16
	global_load_dwordx4 v[40:43], v7, s[54:55]
	global_load_dwordx4 v[44:47], v7, s[54:55] offset:16
	s_waitcnt vmcnt(6)
	v_cvt_pk_bf16_f32 v48, v16, v17
	v_cvt_pk_bf16_f32 v49, v18, v19
	v_cvt_pk_bf16_f32 v50, v20, v21
	v_cvt_pk_bf16_f32 v51, v22, v23
	global_store_dwordx4 v3, v[48:51], s[56:57]
	s_waitcnt vmcnt(4)
	v_cvt_pk_bf16_f32 v52, v24, v25
	v_cvt_pk_bf16_f32 v53, v26, v27
	v_cvt_pk_bf16_f32 v54, v28, v29
	v_cvt_pk_bf16_f32 v55, v30, v31
	global_store_dwordx4 v9, v[52:55], s[56:57]
	s_waitcnt vmcnt(2)
	v_cvt_pk_bf16_f32 v48, v32, v33
	v_cvt_pk_bf16_f32 v49, v34, v35
	v_cvt_pk_bf16_f32 v50, v36, v37
	v_cvt_pk_bf16_f32 v51, v38, v39
	global_store_dwordx4 v10, v[48:51], s[56:57]
	s_waitcnt vmcnt(0)
	v_cvt_pk_bf16_f32 v52, v40, v41
	v_cvt_pk_bf16_f32 v53, v42, v43
	v_cvt_pk_bf16_f32 v54, v44, v45
	v_cvt_pk_bf16_f32 v55, v46, v47
	global_store_dwordx4 v11, v[52:55], s[56:57]
.Ldef_next:
	s_add_u32 s50, s50, s51
	s_branch .Ldef_loop
.Ldef_done:
	s_branch .LBB0_485
.Lscan_go:
	v_mov_b32_e32 v123, v220
	s_movk_i32 s0, 0x800
	s_waitcnt vmcnt(0) lgkmcnt(0)
	v_cmp_gt_i32_e32 vcc, s0, v123
	s_barrier
	s_and_saveexec_b64 s[0:1], vcc
	s_cbranch_execz .LBB0_482
	v_add_u32_e32 v0, 0xffffff00, v123
	v_lshlrev_b32_e32 v1, 2, v123
	s_mov_b64 s[2:3], 0
	v_mov_b32_e32 v2, 0
	s_movk_i32 s4, 0x6ff
